# prologue de-serialisation: FoX unit prefix of forget totals loaded in one round trip instead of a serial 7-load loop before the unit barrier
# speedup vs baseline: 1.0007x; 1.0007x over previous
; template <int VAR>
; __device__ __forceinline__ void attn_unit(LAS unsigned char* lds, const AttnArgs& A, int b, int h, int qb, const int tid) {
;     ...
;         if (tid < 8) { float s = 0.f; for (int c = 0; c < tid; ++c) s += A.CT[(b * 8 + c) * 4 + h]; PFX[tid] = s; }
;         __syncthreads();
.LBB0_504:
	s_andn2_b64 vcc, exec, s[8:9]
	s_cbranch_vccnz .LBB0_421
	v_readfirstlane_b32 s70, v124
	v_cmp_gt_i32_e32 vcc, 8, v124
	s_and_saveexec_b64 s[8:9], vcc
	s_cbranch_execz .LBB0_511
	v_cmp_lt_i32_e32 vcc, 0, v124
	v_mov_b32_e32 v0, 0
	s_and_saveexec_b64 s[10:11], vcc
	s_cbranch_execz .LBB0_510
	s_lshl_b32 s12, s72, 2
	s_lshl_b32 s13, s73, 7
	s_or_b32 s12, s13, s12
	s_add_u32 s12, s76, s12
	s_addc_u32 s13, s77, 0
	s_waitcnt lgkmcnt(5)
	global_load_dword v206, v1, s[12:13]
	global_load_dword v207, v1, s[12:13] offset:16
	global_load_dword v208, v1, s[12:13] offset:32
	global_load_dword v209, v1, s[12:13] offset:48
	global_load_dword v210, v1, s[12:13] offset:64
	global_load_dword v211, v1, s[12:13] offset:80
	global_load_dword v212, v1, s[12:13] offset:96
	v_mov_b32_e32 v0, 0
	s_waitcnt vmcnt(0)
	v_cmp_lt_u32_e32 vcc, 0, v124
	s_nop 1
	v_cndmask_b32_e32 v2, 0, v206, vcc
	v_add_f32_e32 v0, v0, v2
	v_cmp_lt_u32_e32 vcc, 1, v124
	s_nop 1
	v_cndmask_b32_e32 v2, 0, v207, vcc
	v_add_f32_e32 v0, v0, v2
	v_cmp_lt_u32_e32 vcc, 2, v124
	s_nop 1
	v_cndmask_b32_e32 v2, 0, v208, vcc
	v_add_f32_e32 v0, v0, v2
	v_cmp_lt_u32_e32 vcc, 3, v124
	s_nop 1
	v_cndmask_b32_e32 v2, 0, v209, vcc
	v_add_f32_e32 v0, v0, v2
	v_cmp_lt_u32_e32 vcc, 4, v124
	s_nop 1
	v_cndmask_b32_e32 v2, 0, v210, vcc
	v_add_f32_e32 v0, v0, v2
	v_cmp_lt_u32_e32 vcc, 5, v124
	s_nop 1
	v_cndmask_b32_e32 v2, 0, v211, vcc
	v_add_f32_e32 v0, v0, v2
	v_cmp_lt_u32_e32 vcc, 6, v124
	s_nop 1
	v_cndmask_b32_e32 v2, 0, v212, vcc
	v_add_f32_e32 v0, v0, v2
